# prep loop (c): each item touches the cache lines of the thread's next item with two unwaited dword loads issued after its own data loads
# speedup vs baseline: 1.0031x; 1.0031x over previous
.LBB0_360:
	s_or_b64 exec, exec, s[0:1]
	v_readlane_b32 s0, v253, 25
	s_mov_b64 s[40:41], 0
	v_mov_b32_e32 v78, v58
	v_lshl_add_u32 v77, v59, 4, s0
	v_and_b32_e32 v116, 0x1c0, v77
	v_and_b32_e32 v117, 24, v76
	v_add_lshl_u32 v116, v116, v117, 2
	v_readlane_b32 s8, v254, 50
	v_readlane_b32 s9, v254, 51
	v_readlane_b32 s12, v254, 52
	v_readlane_b32 s13, v254, 53
	s_nop 0
	s_add_u32 s10, s8, 0x1000
	s_addc_u32 s11, s9, 0
	s_nop 4
	global_load_dwordx4 v[84:87], v116, s[8:9] offset:1024
	global_load_dwordx4 v[88:91], v116, s[8:9] offset:1040
	global_load_dwordx4 v[92:95], v116, s[8:9] offset:1152
	global_load_dwordx4 v[96:99], v116, s[8:9] offset:1168
	global_load_dwordx4 v[100:103], v116, s[10:11]
	global_load_dwordx4 v[104:107], v116, s[10:11] offset:16
	global_load_dwordx4 v[108:111], v116, s[10:11] offset:128
	global_load_dwordx4 v[112:115], v116, s[10:11] offset:144
	global_load_dwordx4 v[120:123], v116, s[10:11] offset:3072
	global_load_dwordx4 v[124:127], v116, s[10:11] offset:3088
	global_load_dwordx4 v[130:133], v116, s[10:11] offset:3200
	global_load_dwordx4 v[164:167], v116, s[10:11] offset:3216
	global_load_dwordx4 v[168:171], v116, s[12:13] offset:1024
	global_load_dwordx4 v[172:175], v116, s[12:13] offset:1040
	global_load_dwordx4 v[176:179], v116, s[12:13] offset:1152
	global_load_dwordx4 v[180:183], v116, s[12:13] offset:1168
	s_waitcnt vmcnt(0)
	s_lshr_b32 s35, s34, 5
	s_mulk_i32 s35, 0x1c00
	s_mov_b32 s32, 0x10ffc0
	v_mov_b32_e32 v205, s35
	v_add_u32_e32 v204, 0xffffe400, v205
	v_add_u32_e32 v206, 0x1c00, v205
	v_cmp_gt_u32_e64 s[30:31], 32, v220
	v_mov_b32_e32 v191, 0
	v_mov_b32_e32 v193, 0
	v_cndmask_b32_e64 v204, v206, v204, s[30:31]
	s_branch .LBB0_363

.LBB0_363:
	v_and_b32_e32 v5, 0x1c0, v77
	v_and_b32_e32 v79, 24, v76
	v_or_b32_e32 v0, v5, v79
	v_ashrrev_i32_e32 v80, 5, v78
	s_mov_b32 s0, 0x8000
	v_add_u32_e32 v4, 0x100, v0
	v_mov_b64_e32 v[0:1], s[70:71]
	v_cmp_gt_i32_e64 s[6:7], s0, v80
	v_mad_i64_i32 v[0:1], s[2:3], v80, s77, v[0:1]
	s_nop 0
	v_cndmask_b32_e64 v6, v222, v223, s[6:7]
	s_mov_b64 s[2:3], 0x1400
	v_and_b32_e32 v7, v6, v80
	v_lshl_add_u64 v[0:1], v[0:1], 0, s[2:3]
	v_lshlrev_b32_e32 v68, 1, v4
	v_mov_b32_e32 v69, v9
	v_mov_b32_e32 v14, 0
	v_cmp_ne_u32_e64 s[0:1], 0, v7
	v_lshl_add_u64 v[2:3], v[0:1], 0, v[68:69]
	v_add_u32_e32 v192, s34, v78
	v_cmp_gt_i32_e64 s[30:31], s32, v192
	s_nop 1
	v_cndmask_b32_e64 v190, 0, v205, s[30:31]
	v_cndmask_b32_e64 v192, 0, v204, s[30:31]
	v_lshl_add_u64 v[186:187], v[2:3], 0, v[190:191]
	v_lshl_add_u64 v[188:189], v[2:3], 0, v[192:193]
	v_mov_b32_e32 v18, 0
	v_mov_b32_e32 v19, 0
	v_mov_b32_e32 v20, 0
	v_mov_b32_e32 v21, 0
	s_and_saveexec_b64 s[4:5], s[0:1]
	s_cbranch_execz .LBB0_365
	v_add_co_u32_e32 v10, vcc, 0xfffff000, v2
	s_nop 1
	v_addc_co_u32_e32 v11, vcc, -1, v3, vcc
	global_load_dwordx4 v[18:21], v[10:11], off offset:-3072

.LBB0_371:
	s_or_b64 exec, exec, s[0:1]
	global_load_dword v184, v[186:187], off
	global_load_dword v185, v[188:189], off
	s_waitcnt vmcnt(5)
	v_lshlrev_b32_e32 v64, 16, v22
	v_and_b32_e32 v65, 0xffff0000, v22
	v_lshlrev_b32_e32 v66, 16, v18
	v_and_b32_e32 v67, 0xffff0000, v18
	s_waitcnt vmcnt(5)
	v_pk_mul_f32 v[42:43], v[42:43], v[64:65]
	v_lshlrev_b32_e32 v82, 16, v14
	v_and_b32_e32 v83, 0xffff0000, v14
	s_waitcnt vmcnt(5)
	v_pk_fma_f32 v[42:43], v[50:51], v[66:67], v[42:43]
	v_readlane_b32 s0, v254, 52
	v_pk_fma_f32 v[42:43], v[46:47], v[82:83], v[42:43]
	v_readlane_b32 s1, v254, 53
	s_waitcnt vmcnt(3)
	v_pk_add_f32 v[42:43], v[54:55], v[42:43]
	v_lshl_add_u64 v[60:61], s[0:1], 0, v[8:9]
	v_mul_f32_e32 v8, 0xbfb8aa3b, v42
	v_exp_f32_e32 v46, v8
	v_mul_f32_e32 v8, 0xbfb8aa3b, v43
	v_exp_f32_e32 v47, v8
	s_nop 0
	v_pk_add_f32 v[46:47], v[46:47], 1.0 op_sel_hi:[1,0]
	s_nop 0
	v_div_scale_f32 v8, s[0:1], v47, v47, v43
	v_rcp_f32_e32 v14, v8
	s_nop 0
	v_fma_f32 v18, -v8, v14, 1.0
	v_fmac_f32_e32 v14, v18, v14
	v_div_scale_f32 v18, vcc, v43, v47, v43
	v_mul_f32_e32 v22, v18, v14
	v_fma_f32 v50, -v8, v22, v18
	v_fmac_f32_e32 v22, v50, v14
	v_fma_f32 v8, -v8, v22, v18
	v_div_fmas_f32 v8, v8, v14, v22
	v_div_fixup_f32 v47, v8, v47, v43
	v_div_scale_f32 v8, s[0:1], v46, v46, v42
	v_rcp_f32_e32 v14, v8
	s_nop 0
	v_fma_f32 v18, -v8, v14, 1.0
	v_fmac_f32_e32 v14, v18, v14
	v_div_scale_f32 v18, vcc, v42, v46, v42
	v_mul_f32_e32 v22, v18, v14
	v_fma_f32 v43, -v8, v22, v18
	v_fmac_f32_e32 v22, v43, v14
	v_fma_f32 v8, -v8, v22, v18
	v_div_fmas_f32 v8, v8, v14, v22
	v_lshlrev_b32_e32 v22, 16, v23
	v_and_b32_e32 v23, 0xffff0000, v23
	v_lshlrev_b32_e32 v18, 16, v19
	v_and_b32_e32 v19, 0xffff0000, v19
	v_pk_mul_f32 v[22:23], v[44:45], v[22:23]
	v_lshlrev_b32_e32 v14, 16, v15
	v_and_b32_e32 v15, 0xffff0000, v15
	v_pk_fma_f32 v[18:19], v[52:53], v[18:19], v[22:23]
	v_div_fixup_f32 v46, v8, v46, v42
	v_pk_fma_f32 v[14:15], v[48:49], v[14:15], v[18:19]
	s_waitcnt vmcnt(2)
	v_lshlrev_b32_e32 v52, 16, v7
	v_pk_add_f32 v[14:15], v[56:57], v[14:15]
	s_nop 0
	v_mul_f32_e32 v8, 0xbfb8aa3b, v14
	v_exp_f32_e32 v18, v8
	v_mul_f32_e32 v8, 0xbfb8aa3b, v15
	v_exp_f32_e32 v19, v8
	s_nop 0
	v_pk_add_f32 v[18:19], v[18:19], 1.0 op_sel_hi:[1,0]
	s_nop 0
	v_div_scale_f32 v8, s[0:1], v19, v19, v15
	v_rcp_f32_e32 v22, v8
	s_nop 0
	v_fma_f32 v23, -v8, v22, 1.0
	v_fmac_f32_e32 v22, v23, v22
	v_div_scale_f32 v23, vcc, v15, v19, v15
	v_mul_f32_e32 v42, v23, v22
	v_fma_f32 v43, -v8, v42, v23
	v_fmac_f32_e32 v42, v43, v22
	v_fma_f32 v8, -v8, v42, v23
	v_div_fmas_f32 v8, v8, v22, v42
	v_div_fixup_f32 v45, v8, v19, v15
	v_div_scale_f32 v8, s[0:1], v18, v18, v14
	v_rcp_f32_e32 v15, v8
	s_nop 0
	v_fma_f32 v19, -v8, v15, 1.0
	v_fmac_f32_e32 v15, v19, v15
	v_div_scale_f32 v19, vcc, v14, v18, v14
	v_mul_f32_e32 v22, v19, v15
	v_fma_f32 v23, -v8, v22, v19
	v_fmac_f32_e32 v22, v23, v15
	v_fma_f32 v8, -v8, v22, v19
	v_div_fmas_f32 v8, v8, v15, v22
	v_div_fixup_f32 v44, v8, v18, v14
	v_lshlrev_b32_e32 v14, 16, v24
	v_and_b32_e32 v15, 0xffff0000, v24
	v_lshlrev_b32_e32 v18, 16, v20
	v_and_b32_e32 v19, 0xffff0000, v20
	v_pk_mul_f32 v[14:15], v[26:27], v[14:15]
	v_lshlrev_b32_e32 v22, 16, v16
	v_and_b32_e32 v23, 0xffff0000, v16
	v_pk_fma_f32 v[14:15], v[38:39], v[18:19], v[14:15]
	v_lshlrev_b32_e32 v24, 16, v0
	v_pk_fma_f32 v[14:15], v[30:31], v[22:23], v[14:15]
	s_nop 0
	v_pk_add_f32 v[14:15], v[34:35], v[14:15]
	s_nop 0
	v_mul_f32_e32 v8, 0xbfb8aa3b, v14
	v_exp_f32_e32 v18, v8
	v_mul_f32_e32 v8, 0xbfb8aa3b, v15
	v_exp_f32_e32 v19, v8
	s_nop 0
	v_pk_add_f32 v[18:19], v[18:19], 1.0 op_sel_hi:[1,0]
	s_nop 0
	v_div_scale_f32 v8, s[0:1], v19, v19, v15
	v_rcp_f32_e32 v16, v8
	s_nop 0
	v_fma_f32 v20, -v8, v16, 1.0
	v_fmac_f32_e32 v16, v20, v16
	v_div_scale_f32 v20, vcc, v15, v19, v15
	v_mul_f32_e32 v22, v20, v16
	v_fma_f32 v23, -v8, v22, v20
	v_fmac_f32_e32 v22, v23, v16
	v_fma_f32 v8, -v8, v22, v20
	v_div_fmas_f32 v8, v8, v16, v22
	v_div_fixup_f32 v49, v8, v19, v15
	v_div_scale_f32 v8, s[0:1], v18, v18, v14
	v_rcp_f32_e32 v15, v8
	v_lshlrev_b32_e32 v22, 16, v10
	v_and_b32_e32 v23, 0xffff0000, v10
	v_fma_f32 v16, -v8, v15, 1.0
	v_fmac_f32_e32 v15, v16, v15
	v_div_scale_f32 v16, vcc, v14, v18, v14
	v_mul_f32_e32 v19, v16, v15
	v_fma_f32 v20, -v8, v19, v16
	v_fmac_f32_e32 v19, v20, v15
	v_fma_f32 v8, -v8, v19, v16
	v_div_fmas_f32 v8, v8, v15, v19
	v_div_fixup_f32 v48, v8, v18, v14
	v_lshlrev_b32_e32 v14, 16, v25
	v_and_b32_e32 v15, 0xffff0000, v25
	v_lshlrev_b32_e32 v18, 16, v21
	v_and_b32_e32 v19, 0xffff0000, v21
	v_pk_mul_f32 v[14:15], v[28:29], v[14:15]
	v_lshlrev_b32_e32 v16, 16, v17
	v_and_b32_e32 v17, 0xffff0000, v17
	v_pk_fma_f32 v[14:15], v[40:41], v[18:19], v[14:15]
	v_and_b32_e32 v25, 0xffff0000, v0
	v_pk_fma_f32 v[14:15], v[32:33], v[16:17], v[14:15]
	v_lshlrev_b32_e32 v40, 16, v4
	v_pk_add_f32 v[14:15], v[36:37], v[14:15]
	v_and_b32_e32 v41, 0xffff0000, v4
	v_mul_f32_e32 v8, 0xbfb8aa3b, v14
	v_exp_f32_e32 v16, v8
	v_mul_f32_e32 v8, 0xbfb8aa3b, v15
	v_exp_f32_e32 v17, v8
	s_nop 0
	v_pk_add_f32 v[16:17], v[16:17], 1.0 op_sel_hi:[1,0]
	s_nop 0
	v_div_scale_f32 v8, s[0:1], v17, v17, v15
	v_rcp_f32_e32 v18, v8
	s_nop 0
	v_fma_f32 v19, -v8, v18, 1.0
	v_fmac_f32_e32 v18, v19, v18
	v_div_scale_f32 v19, vcc, v15, v17, v15
	v_mul_f32_e32 v20, v19, v18
	v_fma_f32 v21, -v8, v20, v19
	v_fmac_f32_e32 v20, v21, v18
	v_fma_f32 v8, -v8, v20, v19
	v_div_fmas_f32 v8, v8, v18, v20
	v_div_fixup_f32 v51, v8, v17, v15
	v_div_scale_f32 v8, s[0:1], v16, v16, v14
	v_rcp_f32_e32 v15, v8
	s_mov_b64 s[0:1], 0x480
	v_lshl_add_u64 v[66:67], v[62:63], 0, s[0:1]
	s_mov_b64 s[0:1], 0x1c80
	v_fma_f32 v17, -v8, v15, 1.0
	v_fmac_f32_e32 v15, v17, v15
	v_div_scale_f32 v17, vcc, v14, v16, v14
	v_mul_f32_e32 v18, v17, v15
	v_fma_f32 v19, -v8, v18, v17
	v_fmac_f32_e32 v18, v19, v15
	v_fma_f32 v8, -v8, v18, v17
	v_div_fmas_f32 v8, v8, v15, v18
	v_div_fixup_f32 v50, v8, v16, v14
	v_mov_b64_e32 v[14:15], v[96:97]
	v_mov_b64_e32 v[16:17], v[98:99]
	v_mov_b64_e32 v[28:29], v[92:93]
	v_mov_b64_e32 v[30:31], v[94:95]
	v_mov_b64_e32 v[18:19], v[112:113]
	v_mov_b64_e32 v[20:21], v[114:115]
	v_mov_b64_e32 v[32:33], v[108:109]
	v_mov_b64_e32 v[34:35], v[110:111]
	v_lshl_add_u64 v[64:65], v[62:63], 0, s[0:1]
	s_movk_i32 s0, 0x1000
	v_lshlrev_b32_e32 v8, 16, v3
	s_waitcnt vmcnt(2)
	v_pk_mul_f32 v[22:23], v[32:33], v[22:23]
	s_nop 0
	v_pk_fma_f32 v[22:23], v[28:29], v[24:25], v[22:23]
	v_add_co_u32_e32 v24, vcc, s0, v62
	s_nop 1
	v_addc_co_u32_e32 v25, vcc, 0, v63, vcc
	v_mov_b64_e32 v[36:37], v[130:131]
	v_mov_b64_e32 v[38:39], v[132:133]
	v_mov_b64_e32 v[26:27], v[164:165]
	v_mov_b64_e32 v[28:29], v[166:167]
	s_waitcnt vmcnt(2)
	v_pk_fma_f32 v[32:33], v[36:37], v[40:41], v[22:23]
	v_mov_b64_e32 v[22:23], v[180:181]
	v_mov_b64_e32 v[24:25], v[182:183]
	v_mov_b64_e32 v[40:41], v[176:177]
	v_mov_b64_e32 v[42:43], v[178:179]
	s_waitcnt vmcnt(2)
	v_pk_add_f32 v[32:33], v[40:41], v[32:33]
	s_nop 0
	v_mul_f32_e32 v0, 0xbfb8aa3b, v32
	v_exp_f32_e32 v36, v0
	v_mul_f32_e32 v0, 0xbfb8aa3b, v33
	v_exp_f32_e32 v37, v0
	s_nop 0
	v_pk_add_f32 v[36:37], v[36:37], 1.0 op_sel_hi:[1,0]
	s_nop 0
	v_div_scale_f32 v0, s[0:1], v37, v37, v33
	v_rcp_f32_e32 v4, v0
	s_nop 0
	v_fma_f32 v10, -v0, v4, 1.0
	v_fmac_f32_e32 v4, v10, v4
	v_div_scale_f32 v10, vcc, v33, v37, v33
	v_mul_f32_e32 v40, v10, v4
	v_fma_f32 v41, -v0, v40, v10
	v_fmac_f32_e32 v40, v41, v4
	v_fma_f32 v0, -v0, v40, v10
	v_div_fmas_f32 v0, v0, v4, v40
	v_div_fixup_f32 v33, v0, v37, v33
	v_div_scale_f32 v0, s[0:1], v36, v36, v32
	v_rcp_f32_e32 v4, v0
	s_nop 0
	v_fma_f32 v10, -v0, v4, 1.0
	v_fmac_f32_e32 v4, v10, v4
	v_div_scale_f32 v10, vcc, v32, v36, v32
	v_mul_f32_e32 v37, v10, v4
	v_fma_f32 v40, -v0, v37, v10
	v_fmac_f32_e32 v37, v40, v4
	v_fma_f32 v0, -v0, v37, v10
	v_div_fmas_f32 v0, v0, v4, v37
	v_lshlrev_b32_e32 v10, 16, v11
	v_and_b32_e32 v11, 0xffff0000, v11
	v_div_fixup_f32 v32, v0, v36, v32
	v_lshlrev_b32_e32 v0, 16, v1
	v_and_b32_e32 v1, 0xffff0000, v1
	v_pk_mul_f32 v[10:11], v[34:35], v[10:11]
	v_lshlrev_b32_e32 v4, 16, v5
	v_and_b32_e32 v5, 0xffff0000, v5
	v_pk_fma_f32 v[0:1], v[30:31], v[0:1], v[10:11]
	s_nop 0
	v_pk_fma_f32 v[0:1], v[38:39], v[4:5], v[0:1]
	s_nop 0
	v_pk_add_f32 v[0:1], v[42:43], v[0:1]
	s_nop 0
	v_mul_f32_e32 v4, 0xbfb8aa3b, v0
	v_mul_f32_e32 v5, 0xbfb8aa3b, v1
	v_exp_f32_e32 v4, v4
	v_exp_f32_e32 v5, v5
	s_nop 0
	v_pk_add_f32 v[4:5], v[4:5], 1.0 op_sel_hi:[1,0]
	s_nop 0
	v_div_scale_f32 v10, s[0:1], v5, v5, v1
	v_rcp_f32_e32 v11, v10
	s_nop 0
	v_fma_f32 v30, -v10, v11, 1.0
	v_fmac_f32_e32 v11, v30, v11
	v_div_scale_f32 v30, vcc, v1, v5, v1
	v_mul_f32_e32 v31, v30, v11
	v_fma_f32 v34, -v10, v31, v30
	v_fmac_f32_e32 v31, v34, v11
	v_fma_f32 v10, -v10, v31, v30
	v_div_fmas_f32 v10, v10, v11, v31
	v_div_fixup_f32 v1, v10, v5, v1
	v_div_scale_f32 v5, s[0:1], v4, v4, v0
	v_rcp_f32_e32 v10, v5
	s_nop 0
	v_fma_f32 v11, -v5, v10, 1.0
	v_fmac_f32_e32 v10, v11, v10
	v_div_scale_f32 v11, vcc, v0, v4, v0
	v_mul_f32_e32 v30, v11, v10
	v_fma_f32 v31, -v5, v30, v11
	v_fmac_f32_e32 v30, v31, v10
	v_fma_f32 v5, -v5, v30, v11
	v_div_fmas_f32 v5, v5, v10, v30
	v_div_fixup_f32 v0, v5, v4, v0
	v_lshlrev_b32_e32 v4, 16, v12
	v_and_b32_e32 v5, 0xffff0000, v12
	v_lshlrev_b32_e32 v10, 16, v2
	v_and_b32_e32 v11, 0xffff0000, v2
	v_pk_mul_f32 v[4:5], v[18:19], v[4:5]
	v_lshlrev_b32_e32 v30, 16, v6
	v_and_b32_e32 v31, 0xffff0000, v6
	v_pk_fma_f32 v[4:5], v[14:15], v[10:11], v[4:5]
	s_nop 0
	v_pk_fma_f32 v[4:5], v[26:27], v[30:31], v[4:5]
	s_nop 0
	v_pk_add_f32 v[4:5], v[22:23], v[4:5]
	s_nop 0
	v_mul_f32_e32 v2, 0xbfb8aa3b, v4
	v_exp_f32_e32 v10, v2
	v_mul_f32_e32 v2, 0xbfb8aa3b, v5
	v_exp_f32_e32 v11, v2
	s_nop 0
	v_pk_add_f32 v[10:11], v[10:11], 1.0 op_sel_hi:[1,0]
	s_nop 0
	v_div_scale_f32 v2, s[0:1], v11, v11, v5
	v_rcp_f32_e32 v6, v2
	s_nop 0
	v_fma_f32 v12, -v2, v6, 1.0
	v_fmac_f32_e32 v6, v12, v6
	v_div_scale_f32 v12, vcc, v5, v11, v5
	v_mul_f32_e32 v14, v12, v6
	v_fma_f32 v15, -v2, v14, v12
	v_fmac_f32_e32 v14, v15, v6
	v_fma_f32 v2, -v2, v14, v12
	v_div_fmas_f32 v2, v2, v6, v14
	v_div_fixup_f32 v5, v2, v11, v5
	v_div_scale_f32 v2, s[0:1], v10, v10, v4
	v_rcp_f32_e32 v6, v2
	s_nop 0
	v_fma_f32 v11, -v2, v6, 1.0
	v_fmac_f32_e32 v6, v11, v6
	v_div_scale_f32 v11, vcc, v4, v10, v4
	v_mul_f32_e32 v12, v11, v6
	v_fma_f32 v14, -v2, v12, v11
	v_fmac_f32_e32 v12, v14, v6
	v_fma_f32 v2, -v2, v12, v11
	v_div_fmas_f32 v2, v2, v6, v12
	v_div_fixup_f32 v4, v2, v10, v4
	v_mul_f32_e32 v6, v28, v52
	v_and_b32_e32 v11, 0xffff0000, v7
	v_and_b32_e32 v10, 0xffff0000, v3
	v_mov_b32_e32 v28, v17
	v_pk_mul_f32 v[10:11], v[28:29], v[10:11]
	v_mul_f32_e32 v2, v16, v8
	v_lshlrev_b32_e32 v12, 16, v13
	v_and_b32_e32 v13, 0xffff0000, v13
	v_mov_b32_e32 v3, v10
	v_pk_fma_f32 v[2:3], v[20:21], v[12:13], v[2:3]
	v_mov_b32_e32 v7, v11
	v_pk_add_f32 v[2:3], v[2:3], v[6:7]
	s_nop 0
	v_pk_add_f32 v[2:3], v[24:25], v[2:3]
	s_nop 0
	v_mul_f32_e32 v6, 0xbfb8aa3b, v2
	v_mul_f32_e32 v7, 0xbfb8aa3b, v3
	v_exp_f32_e32 v6, v6
	v_exp_f32_e32 v7, v7
	s_nop 0
	v_pk_add_f32 v[6:7], v[6:7], 1.0 op_sel_hi:[1,0]
	s_nop 0
	v_div_scale_f32 v8, s[0:1], v7, v7, v3
	v_rcp_f32_e32 v10, v8
	s_nop 0
	v_fma_f32 v11, -v8, v10, 1.0
	v_fmac_f32_e32 v10, v11, v10
	v_div_scale_f32 v11, vcc, v3, v7, v3
	v_mul_f32_e32 v12, v11, v10
	v_fma_f32 v13, -v8, v12, v11
	v_fmac_f32_e32 v12, v13, v10
	v_fma_f32 v8, -v8, v12, v11
	v_div_fmas_f32 v8, v8, v10, v12
	v_div_fixup_f32 v3, v8, v7, v3
	v_div_scale_f32 v7, s[0:1], v6, v6, v2
	v_rcp_f32_e32 v8, v7
	s_nop 0
	v_fma_f32 v10, -v7, v8, 1.0
	v_fmac_f32_e32 v8, v10, v8
	v_div_scale_f32 v10, vcc, v2, v6, v2
	v_mul_f32_e32 v11, v10, v8
	v_fma_f32 v12, -v7, v11, v10
	v_fmac_f32_e32 v11, v12, v8
	v_fma_f32 v7, -v7, v11, v10
	v_div_fmas_f32 v7, v7, v8, v11
	v_div_fixup_f32 v2, v7, v6, v2
	s_and_saveexec_b64 s[0:1], s[6:7]
	s_cbranch_execz .LBB0_373
	v_and_b32_e32 v6, 4, v78
	v_lshrrev_b32_e32 v7, 6, v80
	v_cmp_eq_u32_e32 vcc, 0, v6
	s_nop 1
	v_cndmask_b32_e32 v6, v80, v7, vcc
	v_lshlrev_b32_e32 v6, 8, v6
	v_and_b32_e32 v6, 0x3f00, v6
	v_lshlrev_b32_e32 v7, 3, v79
	v_add3_u32 v6, 0, v6, v7
	ds_read_b128 v[10:13], v6
	ds_read_b128 v[14:17], v6 offset:16
	ds_read_b128 v[18:21], v6 offset:32
	ds_read_b128 v[22:25], v6 offset:48
	s_waitcnt lgkmcnt(3)
	v_mov_b32_e32 v7, v12
	v_mov_b32_e32 v12, v11
	v_mov_b32_e32 v6, v10
	v_pk_mul_f32 v[10:11], v[32:33], v[12:13]
	s_waitcnt lgkmcnt(0)
	v_mov_b32_e32 v8, v23
	v_pk_fma_f32 v[10:11], v[46:47], v[6:7], v[10:11] neg_lo:[0,0,1] neg_hi:[0,0,1]
	v_pk_mul_f32 v[6:7], v[32:33], v[6:7]
	s_nop 0
	v_pk_fma_f32 v[32:33], v[46:47], v[12:13], v[6:7]
	v_mov_b32_e32 v7, v16
	v_mov_b32_e32 v16, v15
	v_mov_b32_e32 v6, v14
	v_pk_mul_f32 v[12:13], v[0:1], v[16:17]
	v_pk_mul_f32 v[0:1], v[0:1], v[6:7]
	v_pk_fma_f32 v[12:13], v[44:45], v[6:7], v[12:13] neg_lo:[0,0,1] neg_hi:[0,0,1]
	v_mov_b32_e32 v6, v18
	v_mov_b32_e32 v7, v20
	v_mov_b32_e32 v20, v19
	v_pk_mul_f32 v[14:15], v[4:5], v[20:21]
	v_pk_mul_f32 v[4:5], v[4:5], v[6:7]
	v_pk_fma_f32 v[0:1], v[44:45], v[16:17], v[0:1]
	v_pk_fma_f32 v[4:5], v[48:49], v[20:21], v[4:5]
	v_pk_mul_f32 v[16:17], v[2:3], v[8:9]
	v_pk_mul_f32 v[20:21], v[2:3], v[22:23]
	v_mov_b32_e32 v2, v51
	v_pk_fma_f32 v[14:15], v[48:49], v[6:7], v[14:15] neg_lo:[0,0,1] neg_hi:[0,0,1]
	v_pk_mul_f32 v[6:7], v[50:51], v[22:23]
	v_pk_mul_f32 v[18:19], v[50:51], v[8:9]
	v_pk_mul_f32 v[22:23], v[2:3], v[24:25]
	v_mov_b32_e32 v50, v3
	v_mov_b32_e32 v7, v22
	v_mov_b32_e32 v17, v23
	v_pk_mul_f32 v[2:3], v[50:51], v[24:25]
	v_pk_add_f32 v[6:7], v[6:7], v[16:17] neg_lo:[0,1] neg_hi:[0,1]
	v_mov_b32_e32 v19, v3
	v_mov_b32_e32 v21, v2
	v_pk_add_f32 v[2:3], v[18:19], v[20:21]
	v_mov_b64_e32 v[50:51], v[6:7]
	v_mov_b32_e32 v46, v10
	v_mov_b32_e32 v47, v11
	v_mov_b32_e32 v44, v12
	v_mov_b32_e32 v45, v13
	v_mov_b32_e32 v48, v14
	v_mov_b32_e32 v49, v15
.LBB0_373:
	s_or_b64 exec, exec, s[0:1]
	v_readlane_b32 s0, v251, 43
	v_readlane_b32 s1, v251, 44
	v_lshlrev_b32_e32 v8, 1, v69
	v_cvt_pk_bf16_f32 v10, v46, v47
	v_mov_b64_e32 v[6:7], s[0:1]
	s_movk_i32 s0, 0x600
	v_mad_i64_i32 v[6:7], s[0:1], v80, s0, v[6:7]
	v_cvt_pk_bf16_f32 v11, v44, v45
	v_cvt_pk_bf16_f32 v12, v48, v49
	v_cvt_pk_bf16_f32 v13, v50, v51
	v_lshl_add_u64 v[6:7], v[6:7], 0, v[8:9]
	v_add_u32_e32 v80, s34, v78
	s_mov_b32 s0, 0x110000
	global_store_dwordx4 v[6:7], v[10:13], off offset:512
	v_cmp_gt_i32_e32 vcc, s0, v80
	s_mov_b64 s[0:1], -1
	v_cvt_pk_bf16_f32 v10, v32, v33
	v_cvt_pk_bf16_f32 v11, v0, v1
	v_cvt_pk_bf16_f32 v12, v4, v5
	v_cvt_pk_bf16_f32 v13, v2, v3
	global_store_dwordx4 v[6:7], v[10:13], off offset:576
	s_and_saveexec_b64 s[18:19], vcc
	s_cbranch_execz .LBB0_362
	v_ashrrev_i32_e32 v81, 5, v80
	s_mov_b32 s0, 0x8000
	v_mov_b64_e32 v[0:1], s[70:71]
	v_cmp_gt_i32_e64 s[6:7], s0, v81
	v_mad_i64_i32 v[0:1], s[2:3], v81, s77, v[0:1]
	s_nop 0
	v_cndmask_b32_e64 v4, v222, v223, s[6:7]
	s_mov_b64 s[2:3], 0x1400
	v_and_b32_e32 v5, v4, v81
	v_lshl_add_u64 v[0:1], v[0:1], 0, s[2:3]
	v_mov_b32_e32 v69, v9
	v_mov_b32_e32 v14, 0
	v_cmp_ne_u32_e64 s[0:1], 0, v5
	v_lshl_add_u64 v[2:3], v[0:1], 0, v[68:69]
	v_add_u32_e32 v192, s34, v80
	v_cmp_gt_i32_e64 s[30:31], s32, v192
	s_nop 1
	v_cndmask_b32_e64 v190, 0, v205, s[30:31]
	v_cndmask_b32_e64 v192, 0, v204, s[30:31]
	v_lshl_add_u64 v[186:187], v[2:3], 0, v[190:191]
	v_lshl_add_u64 v[188:189], v[2:3], 0, v[192:193]
	v_mov_b32_e32 v18, 0
	v_mov_b32_e32 v19, 0
	v_mov_b32_e32 v20, 0
	v_mov_b32_e32 v21, 0
	s_and_saveexec_b64 s[4:5], s[0:1]
	s_cbranch_execz .LBB0_376
	v_add_co_u32_e32 v6, vcc, 0xfffff000, v2
	s_nop 1
	v_addc_co_u32_e32 v7, vcc, -1, v3, vcc
	global_load_dwordx4 v[18:21], v[6:7], off offset:-3072

.LBB0_382:
	s_or_b64 exec, exec, s[0:1]
	global_load_dword v184, v[186:187], off
	global_load_dword v185, v[188:189], off
	s_waitcnt vmcnt(5)
	v_lshlrev_b32_e32 v68, 16, v22
	v_and_b32_e32 v69, 0xffff0000, v22
	v_lshlrev_b32_e32 v70, 16, v18
	v_and_b32_e32 v71, 0xffff0000, v18
	s_waitcnt vmcnt(5)
	v_pk_mul_f32 v[54:55], v[54:55], v[68:69]
	v_lshlrev_b32_e32 v72, 16, v14
	v_and_b32_e32 v73, 0xffff0000, v14
	v_pk_fma_f32 v[42:43], v[42:43], v[70:71], v[54:55]
	s_waitcnt vmcnt(5)
	v_pk_fma_f32 v[42:43], v[46:47], v[72:73], v[42:43]
	s_waitcnt vmcnt(3)
	v_pk_add_f32 v[42:43], v[50:51], v[42:43]
	s_nop 0
	v_mul_f32_e32 v14, 0xbfb8aa3b, v42
	v_exp_f32_e32 v46, v14
	v_mul_f32_e32 v14, 0xbfb8aa3b, v43
	v_exp_f32_e32 v47, v14
	s_nop 0
	v_pk_add_f32 v[46:47], v[46:47], 1.0 op_sel_hi:[1,0]
	s_nop 0
	v_div_scale_f32 v14, s[0:1], v47, v47, v43
	v_rcp_f32_e32 v18, v14
	s_nop 0
	v_fma_f32 v22, -v14, v18, 1.0
	v_fmac_f32_e32 v18, v22, v18
	v_div_scale_f32 v22, vcc, v43, v47, v43
	v_mul_f32_e32 v50, v22, v18
	v_fma_f32 v51, -v14, v50, v22
	v_fmac_f32_e32 v50, v51, v18
	v_fma_f32 v14, -v14, v50, v22
	v_div_fmas_f32 v14, v14, v18, v50
	v_div_fixup_f32 v47, v14, v47, v43
	v_div_scale_f32 v14, s[0:1], v46, v46, v42
	v_rcp_f32_e32 v18, v14
	s_nop 0
	v_fma_f32 v22, -v14, v18, 1.0
	v_fmac_f32_e32 v18, v22, v18
	v_div_scale_f32 v22, vcc, v42, v46, v42
	v_mul_f32_e32 v43, v22, v18
	v_fma_f32 v50, -v14, v43, v22
	v_fmac_f32_e32 v43, v50, v18
	v_fma_f32 v14, -v14, v43, v22
	v_lshlrev_b32_e32 v22, 16, v23
	v_and_b32_e32 v23, 0xffff0000, v23
	v_div_fmas_f32 v14, v14, v18, v43
	v_lshlrev_b32_e32 v18, 16, v19
	v_and_b32_e32 v19, 0xffff0000, v19
	v_pk_mul_f32 v[22:23], v[56:57], v[22:23]
	v_div_fixup_f32 v46, v14, v46, v42
	v_lshlrev_b32_e32 v14, 16, v15
	v_and_b32_e32 v15, 0xffff0000, v15
	v_pk_fma_f32 v[18:19], v[44:45], v[18:19], v[22:23]
	s_nop 0
	v_pk_fma_f32 v[14:15], v[48:49], v[14:15], v[18:19]
	s_nop 0
	v_pk_add_f32 v[14:15], v[52:53], v[14:15]
	s_waitcnt vmcnt(2)
	v_lshlrev_b32_e32 v53, 16, v7
	v_mul_f32_e32 v18, 0xbfb8aa3b, v14
	v_mul_f32_e32 v19, 0xbfb8aa3b, v15
	v_exp_f32_e32 v18, v18
	v_exp_f32_e32 v19, v19
	v_lshlrev_b32_e32 v52, 16, v3
	v_pk_add_f32 v[18:19], v[18:19], 1.0 op_sel_hi:[1,0]
	s_nop 0
	v_div_scale_f32 v22, s[0:1], v19, v19, v15
	v_rcp_f32_e32 v23, v22
	s_nop 0
	v_fma_f32 v42, -v22, v23, 1.0
	v_fmac_f32_e32 v23, v42, v23
	v_div_scale_f32 v42, vcc, v15, v19, v15
	v_mul_f32_e32 v43, v42, v23
	v_fma_f32 v44, -v22, v43, v42
	v_fmac_f32_e32 v43, v44, v23
	v_fma_f32 v22, -v22, v43, v42
	v_div_fmas_f32 v22, v22, v23, v43
	v_div_fixup_f32 v45, v22, v19, v15
	v_div_scale_f32 v15, s[0:1], v18, v18, v14
	v_rcp_f32_e32 v19, v15
	s_nop 0
	v_fma_f32 v22, -v15, v19, 1.0
	v_fmac_f32_e32 v19, v22, v19
	v_div_scale_f32 v22, vcc, v14, v18, v14
	v_mul_f32_e32 v23, v22, v19
	v_fma_f32 v42, -v15, v23, v22
	v_fmac_f32_e32 v23, v42, v19
	v_fma_f32 v15, -v15, v23, v22
	v_div_fmas_f32 v15, v15, v19, v23
	v_div_fixup_f32 v44, v15, v18, v14
	v_lshlrev_b32_e32 v14, 16, v24
	v_and_b32_e32 v15, 0xffff0000, v24
	v_lshlrev_b32_e32 v18, 16, v20
	v_and_b32_e32 v19, 0xffff0000, v20
	v_pk_mul_f32 v[14:15], v[30:31], v[14:15]
	v_lshlrev_b32_e32 v22, 16, v16
	v_and_b32_e32 v23, 0xffff0000, v16
	v_pk_fma_f32 v[14:15], v[26:27], v[18:19], v[14:15]
	v_lshlrev_b32_e32 v26, 16, v4
	v_pk_fma_f32 v[14:15], v[34:35], v[22:23], v[14:15]
	v_and_b32_e32 v27, 0xffff0000, v4
	v_pk_add_f32 v[14:15], v[38:39], v[14:15]
	s_nop 0
	v_mul_f32_e32 v16, 0xbfb8aa3b, v14
	v_exp_f32_e32 v18, v16
	v_mul_f32_e32 v16, 0xbfb8aa3b, v15
	v_exp_f32_e32 v19, v16
	s_nop 0
	v_pk_add_f32 v[18:19], v[18:19], 1.0 op_sel_hi:[1,0]
	s_nop 0
	v_div_scale_f32 v16, s[0:1], v19, v19, v15
	v_rcp_f32_e32 v20, v16
	s_nop 0
	v_fma_f32 v22, -v16, v20, 1.0
	v_fmac_f32_e32 v20, v22, v20
	v_div_scale_f32 v22, vcc, v15, v19, v15
	v_mul_f32_e32 v23, v22, v20
	v_fma_f32 v24, -v16, v23, v22
	v_fmac_f32_e32 v23, v24, v20
	v_fma_f32 v16, -v16, v23, v22
	v_div_fmas_f32 v16, v16, v20, v23
	v_div_fixup_f32 v49, v16, v19, v15
	v_div_scale_f32 v15, s[0:1], v18, v18, v14
	v_rcp_f32_e32 v16, v15
	v_and_b32_e32 v23, 0xffff0000, v10
	v_lshlrev_b32_e32 v24, 16, v0
	v_fma_f32 v19, -v15, v16, 1.0
	v_fmac_f32_e32 v16, v19, v16
	v_div_scale_f32 v19, vcc, v14, v18, v14
	v_mul_f32_e32 v20, v19, v16
	v_fma_f32 v22, -v15, v20, v19
	v_fmac_f32_e32 v20, v22, v16
	v_fma_f32 v15, -v15, v20, v19
	v_div_fmas_f32 v15, v15, v16, v20
	v_div_fixup_f32 v48, v15, v18, v14
	v_lshlrev_b32_e32 v14, 16, v25
	v_and_b32_e32 v15, 0xffff0000, v25
	v_lshlrev_b32_e32 v18, 16, v21
	v_and_b32_e32 v19, 0xffff0000, v21
	v_pk_mul_f32 v[14:15], v[32:33], v[14:15]
	v_lshlrev_b32_e32 v16, 16, v17
	v_and_b32_e32 v17, 0xffff0000, v17
	v_pk_fma_f32 v[14:15], v[28:29], v[18:19], v[14:15]
	v_and_b32_e32 v25, 0xffff0000, v0
	v_pk_fma_f32 v[14:15], v[36:37], v[16:17], v[14:15]
	s_nop 0
	v_pk_add_f32 v[14:15], v[40:41], v[14:15]
	s_nop 0
	v_mul_f32_e32 v16, 0xbfb8aa3b, v14
	v_mul_f32_e32 v17, 0xbfb8aa3b, v15
	v_exp_f32_e32 v16, v16
	v_exp_f32_e32 v17, v17
	s_nop 0
	v_pk_add_f32 v[16:17], v[16:17], 1.0 op_sel_hi:[1,0]
	s_nop 0
	v_div_scale_f32 v18, s[0:1], v17, v17, v15
	v_rcp_f32_e32 v19, v18
	s_nop 0
	v_fma_f32 v20, -v18, v19, 1.0
	v_fmac_f32_e32 v19, v20, v19
	v_div_scale_f32 v20, vcc, v15, v17, v15
	v_mul_f32_e32 v21, v20, v19
	v_fma_f32 v22, -v18, v21, v20
	v_fmac_f32_e32 v21, v22, v19
	v_fma_f32 v18, -v18, v21, v20
	v_div_fmas_f32 v18, v18, v19, v21
	v_div_fixup_f32 v51, v18, v17, v15
	v_div_scale_f32 v15, s[0:1], v16, v16, v14
	v_rcp_f32_e32 v17, v15
	v_lshlrev_b32_e32 v22, 16, v10
	v_fma_f32 v18, -v15, v17, 1.0
	v_fmac_f32_e32 v17, v18, v17
	v_div_scale_f32 v18, vcc, v14, v16, v14
	v_mul_f32_e32 v19, v18, v17
	v_fma_f32 v20, -v15, v19, v18
	v_fmac_f32_e32 v19, v20, v17
	v_fma_f32 v15, -v15, v19, v18
	v_div_fmas_f32 v15, v15, v17, v19
	v_div_fixup_f32 v50, v15, v16, v14
	v_mov_b64_e32 v[18:19], v[96:97]
	v_mov_b64_e32 v[20:21], v[98:99]
	v_mov_b64_e32 v[28:29], v[92:93]
	v_mov_b64_e32 v[30:31], v[94:95]
	v_mov_b64_e32 v[14:15], v[112:113]
	v_mov_b64_e32 v[16:17], v[114:115]
	v_mov_b64_e32 v[32:33], v[108:109]
	v_mov_b64_e32 v[34:35], v[110:111]
	s_waitcnt vmcnt(2)
	v_pk_mul_f32 v[22:23], v[32:33], v[22:23]
	s_nop 0
	v_pk_fma_f32 v[28:29], v[28:29], v[24:25], v[22:23]
	v_mov_b64_e32 v[22:23], v[164:165]
	v_mov_b64_e32 v[24:25], v[166:167]
	v_mov_b64_e32 v[36:37], v[130:131]
	v_mov_b64_e32 v[38:39], v[132:133]
	s_waitcnt vmcnt(2)
	v_pk_fma_f32 v[32:33], v[36:37], v[26:27], v[28:29]
	v_mov_b64_e32 v[26:27], v[180:181]
	v_mov_b64_e32 v[28:29], v[182:183]
	v_mov_b64_e32 v[40:41], v[176:177]
	v_mov_b64_e32 v[42:43], v[178:179]
	s_waitcnt vmcnt(2)
	v_pk_add_f32 v[32:33], v[40:41], v[32:33]
	s_nop 0
	v_mul_f32_e32 v0, 0xbfb8aa3b, v32
	v_exp_f32_e32 v36, v0
	v_mul_f32_e32 v0, 0xbfb8aa3b, v33
	v_exp_f32_e32 v37, v0
	s_nop 0
	v_pk_add_f32 v[36:37], v[36:37], 1.0 op_sel_hi:[1,0]
	s_nop 0
	v_div_scale_f32 v0, s[0:1], v37, v37, v33
	v_rcp_f32_e32 v4, v0
	s_nop 0
	v_fma_f32 v10, -v0, v4, 1.0
	v_fmac_f32_e32 v4, v10, v4
	v_div_scale_f32 v10, vcc, v33, v37, v33
	v_mul_f32_e32 v40, v10, v4
	v_fma_f32 v41, -v0, v40, v10
	v_fmac_f32_e32 v40, v41, v4
	v_fma_f32 v0, -v0, v40, v10
	v_div_fmas_f32 v0, v0, v4, v40
	v_div_fixup_f32 v33, v0, v37, v33
	v_div_scale_f32 v0, s[0:1], v36, v36, v32
	v_rcp_f32_e32 v4, v0
	s_nop 0
	v_fma_f32 v10, -v0, v4, 1.0
	v_fmac_f32_e32 v4, v10, v4
	v_div_scale_f32 v10, vcc, v32, v36, v32
	v_mul_f32_e32 v37, v10, v4
	v_fma_f32 v40, -v0, v37, v10
	v_fmac_f32_e32 v37, v40, v4
	v_fma_f32 v0, -v0, v37, v10
	v_div_fmas_f32 v0, v0, v4, v37
	v_lshlrev_b32_e32 v10, 16, v11
	v_and_b32_e32 v11, 0xffff0000, v11
	v_div_fixup_f32 v32, v0, v36, v32
	v_lshlrev_b32_e32 v0, 16, v1
	v_and_b32_e32 v1, 0xffff0000, v1
	v_pk_mul_f32 v[10:11], v[34:35], v[10:11]
	v_lshlrev_b32_e32 v4, 16, v5
	v_and_b32_e32 v5, 0xffff0000, v5
	v_pk_fma_f32 v[0:1], v[30:31], v[0:1], v[10:11]
	s_nop 0
	v_pk_fma_f32 v[0:1], v[38:39], v[4:5], v[0:1]
	s_nop 0
	v_pk_add_f32 v[0:1], v[42:43], v[0:1]
	s_nop 0
	v_mul_f32_e32 v4, 0xbfb8aa3b, v0
	v_mul_f32_e32 v5, 0xbfb8aa3b, v1
	v_exp_f32_e32 v4, v4
	v_exp_f32_e32 v5, v5
	s_nop 0
	v_pk_add_f32 v[4:5], v[4:5], 1.0 op_sel_hi:[1,0]
	s_nop 0
	v_div_scale_f32 v10, s[0:1], v5, v5, v1
	v_rcp_f32_e32 v11, v10
	s_nop 0
	v_fma_f32 v30, -v10, v11, 1.0
	v_fmac_f32_e32 v11, v30, v11
	v_div_scale_f32 v30, vcc, v1, v5, v1
	v_mul_f32_e32 v31, v30, v11
	v_fma_f32 v34, -v10, v31, v30
	v_fmac_f32_e32 v31, v34, v11
	v_fma_f32 v10, -v10, v31, v30
	v_div_fmas_f32 v10, v10, v11, v31
	v_div_fixup_f32 v1, v10, v5, v1
	v_div_scale_f32 v5, s[0:1], v4, v4, v0
	v_rcp_f32_e32 v10, v5
	s_nop 0
	v_fma_f32 v11, -v5, v10, 1.0
	v_fmac_f32_e32 v10, v11, v10
	v_div_scale_f32 v11, vcc, v0, v4, v0
	v_mul_f32_e32 v30, v11, v10
	v_fma_f32 v31, -v5, v30, v11
	v_fmac_f32_e32 v30, v31, v10
	v_fma_f32 v5, -v5, v30, v11
	v_div_fmas_f32 v5, v5, v10, v30
	v_div_fixup_f32 v0, v5, v4, v0
	v_lshlrev_b32_e32 v4, 16, v12
	v_and_b32_e32 v5, 0xffff0000, v12
	v_lshlrev_b32_e32 v10, 16, v2
	v_and_b32_e32 v11, 0xffff0000, v2
	v_pk_mul_f32 v[4:5], v[14:15], v[4:5]
	v_lshlrev_b32_e32 v30, 16, v6
	v_and_b32_e32 v31, 0xffff0000, v6
	v_pk_fma_f32 v[4:5], v[18:19], v[10:11], v[4:5]
	s_nop 0
	v_pk_fma_f32 v[4:5], v[22:23], v[30:31], v[4:5]
	s_nop 0
	v_pk_add_f32 v[4:5], v[26:27], v[4:5]
	s_nop 0
	v_mul_f32_e32 v2, 0xbfb8aa3b, v4
	v_exp_f32_e32 v10, v2
	v_mul_f32_e32 v2, 0xbfb8aa3b, v5
	v_exp_f32_e32 v11, v2
	s_nop 0
	v_pk_add_f32 v[10:11], v[10:11], 1.0 op_sel_hi:[1,0]
	s_nop 0
	v_div_scale_f32 v2, s[0:1], v11, v11, v5
	v_rcp_f32_e32 v6, v2
	s_nop 0
	v_fma_f32 v12, -v2, v6, 1.0
	v_fmac_f32_e32 v6, v12, v6
	v_div_scale_f32 v12, vcc, v5, v11, v5
	v_mul_f32_e32 v14, v12, v6
	v_fma_f32 v15, -v2, v14, v12
	v_fmac_f32_e32 v14, v15, v6
	v_fma_f32 v2, -v2, v14, v12
	v_div_fmas_f32 v2, v2, v6, v14
	v_div_fixup_f32 v5, v2, v11, v5
	v_div_scale_f32 v2, s[0:1], v10, v10, v4
	v_rcp_f32_e32 v6, v2
	s_nop 0
	v_fma_f32 v11, -v2, v6, 1.0
	v_fmac_f32_e32 v6, v11, v6
	v_div_scale_f32 v11, vcc, v4, v10, v4
	v_mul_f32_e32 v12, v11, v6
	v_fma_f32 v14, -v2, v12, v11
	v_fmac_f32_e32 v12, v14, v6
	v_fma_f32 v2, -v2, v12, v11
	v_div_fmas_f32 v2, v2, v6, v12
	v_div_fixup_f32 v4, v2, v10, v4
	v_mul_f32_e32 v6, v24, v53
	v_and_b32_e32 v11, 0xffff0000, v7
	v_and_b32_e32 v10, 0xffff0000, v3
	v_mov_b32_e32 v24, v21
	v_pk_mul_f32 v[10:11], v[24:25], v[10:11]
	v_mul_f32_e32 v2, v20, v52
	v_lshlrev_b32_e32 v12, 16, v13
	v_and_b32_e32 v13, 0xffff0000, v13
	v_mov_b32_e32 v3, v10
	v_pk_fma_f32 v[2:3], v[16:17], v[12:13], v[2:3]
	v_mov_b32_e32 v7, v11
	v_pk_add_f32 v[2:3], v[2:3], v[6:7]
	s_nop 0
	v_pk_add_f32 v[2:3], v[28:29], v[2:3]
	s_nop 0
	v_mul_f32_e32 v6, 0xbfb8aa3b, v2
	v_mul_f32_e32 v7, 0xbfb8aa3b, v3
	v_exp_f32_e32 v6, v6
	v_exp_f32_e32 v7, v7
	s_nop 0
	v_pk_add_f32 v[6:7], v[6:7], 1.0 op_sel_hi:[1,0]
	s_nop 0
	v_div_scale_f32 v10, s[0:1], v7, v7, v3
	v_rcp_f32_e32 v11, v10
	s_nop 0
	v_fma_f32 v12, -v10, v11, 1.0
	v_fmac_f32_e32 v11, v12, v11
	v_div_scale_f32 v12, vcc, v3, v7, v3
	v_mul_f32_e32 v13, v12, v11
	v_fma_f32 v14, -v10, v13, v12
	v_fmac_f32_e32 v13, v14, v11
	v_fma_f32 v10, -v10, v13, v12
	v_div_fmas_f32 v10, v10, v11, v13
	v_div_fixup_f32 v3, v10, v7, v3
	v_div_scale_f32 v7, s[0:1], v6, v6, v2
	v_rcp_f32_e32 v10, v7
	s_nop 0
	v_fma_f32 v11, -v7, v10, 1.0
	v_fmac_f32_e32 v10, v11, v10
	v_div_scale_f32 v11, vcc, v2, v6, v2
	v_mul_f32_e32 v12, v11, v10
	v_fma_f32 v13, -v7, v12, v11
	v_fmac_f32_e32 v12, v13, v10
	v_fma_f32 v7, -v7, v12, v11
	v_div_fmas_f32 v7, v7, v10, v12
	v_div_fixup_f32 v2, v7, v6, v2
	s_and_saveexec_b64 s[0:1], s[6:7]
	s_cbranch_execz .LBB0_361
	v_and_b32_e32 v6, 4, v78
	v_lshrrev_b32_e32 v7, 6, v81
	v_cmp_eq_u32_e32 vcc, 0, v6
	s_nop 1
	v_cndmask_b32_e32 v6, v81, v7, vcc
	v_lshlrev_b32_e32 v6, 8, v6
	v_and_b32_e32 v6, 0x3f00, v6
	v_lshlrev_b32_e32 v7, 3, v79
	v_add3_u32 v6, 0, v6, v7
	ds_read_b128 v[10:13], v6
	ds_read_b128 v[14:17], v6 offset:16
	ds_read_b128 v[18:21], v6 offset:32
	ds_read_b128 v[22:25], v6 offset:48
	s_waitcnt lgkmcnt(3)
	v_mov_b32_e32 v7, v12
	v_mov_b32_e32 v12, v11
	v_mov_b32_e32 v6, v10
	v_pk_mul_f32 v[10:11], v[32:33], v[12:13]
	s_nop 0
	v_pk_fma_f32 v[10:11], v[46:47], v[6:7], v[10:11] neg_lo:[0,0,1] neg_hi:[0,0,1]
	v_pk_mul_f32 v[6:7], v[32:33], v[6:7]
	s_nop 0
	v_pk_fma_f32 v[32:33], v[46:47], v[12:13], v[6:7]
	s_waitcnt lgkmcnt(2)
	v_mov_b32_e32 v7, v16
	v_mov_b32_e32 v16, v15
	v_mov_b32_e32 v6, v14
	v_pk_mul_f32 v[12:13], v[0:1], v[16:17]
	v_pk_mul_f32 v[0:1], v[0:1], v[6:7]
	v_pk_fma_f32 v[12:13], v[44:45], v[6:7], v[12:13] neg_lo:[0,0,1] neg_hi:[0,0,1]
	s_waitcnt lgkmcnt(1)
	v_mov_b32_e32 v6, v18
	v_mov_b32_e32 v7, v20
	v_mov_b32_e32 v20, v19
	v_pk_fma_f32 v[0:1], v[44:45], v[16:17], v[0:1]
	v_pk_mul_f32 v[14:15], v[4:5], v[20:21]
	v_pk_mul_f32 v[4:5], v[4:5], v[6:7]
	s_waitcnt lgkmcnt(0)
	v_mov_b32_e32 v16, v23
	v_pk_fma_f32 v[4:5], v[48:49], v[20:21], v[4:5]
	v_pk_mul_f32 v[18:19], v[2:3], v[16:17]
	v_pk_mul_f32 v[20:21], v[2:3], v[22:23]
	v_mov_b32_e32 v2, v51
	v_pk_fma_f32 v[14:15], v[48:49], v[6:7], v[14:15] neg_lo:[0,0,1] neg_hi:[0,0,1]
	v_pk_mul_f32 v[6:7], v[50:51], v[22:23]
	v_pk_mul_f32 v[16:17], v[50:51], v[16:17]
	v_pk_mul_f32 v[22:23], v[2:3], v[24:25]
	v_mov_b32_e32 v50, v3
	v_mov_b32_e32 v7, v22
	v_mov_b32_e32 v19, v23
	v_pk_mul_f32 v[2:3], v[50:51], v[24:25]
	v_pk_add_f32 v[6:7], v[6:7], v[18:19] neg_lo:[0,1] neg_hi:[0,1]
	v_mov_b32_e32 v17, v3
	v_mov_b32_e32 v21, v2
	v_pk_add_f32 v[2:3], v[16:17], v[20:21]
	v_mov_b64_e32 v[50:51], v[6:7]
	v_mov_b32_e32 v46, v10
	v_mov_b32_e32 v47, v11
	v_mov_b32_e32 v44, v12
	v_mov_b32_e32 v45, v13
	v_mov_b32_e32 v48, v14
	v_mov_b32_e32 v49, v15
	s_branch .LBB0_361
